# E36: E35 + attention-tile row-max reduction with v_permlane16_swap / v_permlane32_swap instead of two dependent ds_bpermute per head
# speedup vs baseline: 1.0085x; 1.0025x over previous
.LBB0_4417:
	v_mov_b32_e32 v78, v3
	s_and_b64 vcc, exec, s[90:91]
	s_nop 1
	v_permlane16_swap_b32_e32 v78, v3
	s_nop 0
	v_max_f32_e32 v3, v3, v78
	v_mov_b32_e32 v78, v3
	s_nop 1
	v_permlane32_swap_b32_e32 v78, v3
	s_nop 0
	v_max3_f32 v78, v4, v3, v78
	v_max_f32_e32 v79, s97, v78
	v_pk_add_f32 v[196:197], v[196:197], v[78:79] op_sel:[0,1] op_sel_hi:[1,1] neg_lo:[0,1] neg_hi:[0,1]
	v_pk_add_f32 v[198:199], v[198:199], v[78:79] op_sel:[0,1] op_sel_hi:[1,1] neg_lo:[0,1] neg_hi:[0,1]
	v_pk_add_f32 v[200:201], v[200:201], v[78:79] op_sel:[0,1] op_sel_hi:[1,1] neg_lo:[0,1] neg_hi:[0,1]
	v_pk_add_f32 v[202:203], v[202:203], v[78:79] op_sel:[0,1] op_sel_hi:[1,1] neg_lo:[0,1] neg_hi:[0,1]
	v_pk_add_f32 v[204:205], v[204:205], v[78:79] op_sel:[0,1] op_sel_hi:[1,1] neg_lo:[0,1] neg_hi:[0,1]
	v_pk_add_f32 v[206:207], v[206:207], v[78:79] op_sel:[0,1] op_sel_hi:[1,1] neg_lo:[0,1] neg_hi:[0,1]
	v_pk_add_f32 v[208:209], v[208:209], v[78:79] op_sel:[0,1] op_sel_hi:[1,1] neg_lo:[0,1] neg_hi:[0,1]
	v_pk_add_f32 v[210:211], v[210:211], v[78:79] op_sel:[0,1] op_sel_hi:[1,1] neg_lo:[0,1] neg_hi:[0,1]
	v_exp_f32_e32 v230, v196
	v_exp_f32_e32 v231, v197
	v_exp_f32_e32 v232, v198
	v_exp_f32_e32 v234, v199
	v_exp_f32_e32 v233, v200
	v_exp_f32_e32 v235, v201
	v_exp_f32_e32 v236, v202
	v_exp_f32_e32 v237, v203
	v_exp_f32_e32 v3, v204
	v_exp_f32_e32 v103, v205
	v_exp_f32_e32 v212, v206
	v_exp_f32_e32 v224, v207
	v_exp_f32_e32 v223, v208
	v_exp_f32_e32 v225, v209
	v_exp_f32_e32 v228, v210
	v_exp_f32_e32 v229, v211
	s_nop 0
	v_pk_add_f32 v[82:83], v[224:225], v[228:229]
	v_pk_add_f32 v[84:85], v[230:231], v[232:233]
	v_pk_add_f32 v[82:83], v[82:83], v[84:85]
	v_pk_add_f32 v[84:85], v[234:235], v[236:237]
	v_pk_add_f32 v[82:83], v[82:83], v[84:85]
	v_add_f32_e32 v80, v82, v83
	v_add_f32_e32 v80, v3, v80
	v_add_f32_e32 v80, v103, v80
	v_add_f32_e32 v80, v212, v80
	v_add_f32_e32 v80, v223, v80
	s_branch .LBB0_4420

.LBB0_4423:
	v_mov_b32_e32 v62, v79
	s_and_b64 vcc, exec, s[90:91]
	s_nop 1
	v_permlane16_swap_b32_e32 v62, v79
	s_nop 0
	v_max_f32_e32 v62, v79, v62
	v_mov_b32_e32 v63, v62
	s_nop 1
	v_permlane32_swap_b32_e32 v63, v62
	s_nop 0
	v_max3_f32 v79, v5, v62, v63
	v_max_f32_e32 v200, s97, v79
	v_pk_add_f32 v[82:83], v[82:83], v[200:201] op_sel_hi:[1,0] neg_lo:[0,1] neg_hi:[0,1]
	v_pk_add_f32 v[84:85], v[84:85], v[200:201] op_sel_hi:[1,0] neg_lo:[0,1] neg_hi:[0,1]
	v_pk_add_f32 v[86:87], v[86:87], v[200:201] op_sel_hi:[1,0] neg_lo:[0,1] neg_hi:[0,1]
	v_pk_add_f32 v[88:89], v[88:89], v[200:201] op_sel_hi:[1,0] neg_lo:[0,1] neg_hi:[0,1]
	v_pk_add_f32 v[90:91], v[90:91], v[200:201] op_sel_hi:[1,0] neg_lo:[0,1] neg_hi:[0,1]
	v_pk_add_f32 v[92:93], v[92:93], v[200:201] op_sel_hi:[1,0] neg_lo:[0,1] neg_hi:[0,1]
	v_pk_add_f32 v[196:197], v[196:197], v[200:201] op_sel_hi:[1,0] neg_lo:[0,1] neg_hi:[0,1]
	v_pk_add_f32 v[198:199], v[198:199], v[200:201] op_sel_hi:[1,0] neg_lo:[0,1] neg_hi:[0,1]
	v_exp_f32_e32 v70, v82
	v_exp_f32_e32 v71, v83
	v_exp_f32_e32 v72, v84
	v_exp_f32_e32 v74, v85
	v_exp_f32_e32 v73, v86
	v_exp_f32_e32 v75, v87
	v_exp_f32_e32 v76, v88
	v_exp_f32_e32 v77, v89
	v_exp_f32_e32 v62, v90
	v_exp_f32_e32 v63, v91
	v_exp_f32_e32 v64, v92
	v_exp_f32_e32 v66, v93
	v_exp_f32_e32 v65, v196
	v_exp_f32_e32 v67, v197
	v_exp_f32_e32 v68, v198
	v_exp_f32_e32 v69, v199
	s_nop 0
	v_pk_add_f32 v[82:83], v[62:63], v[64:65]
	v_pk_add_f32 v[84:85], v[66:67], v[68:69]
	v_pk_add_f32 v[82:83], v[82:83], v[84:85]
	v_pk_add_f32 v[84:85], v[70:71], v[72:73]
	v_pk_add_f32 v[82:83], v[82:83], v[84:85]
	v_pk_add_f32 v[84:85], v[74:75], v[76:77]
	v_pk_add_f32 v[82:83], v[82:83], v[84:85]
	v_add_f32_e32 v81, v82, v83
	s_branch .LBB0_4426

.LBB0_4447:
	v_mov_b32_e32 v3, v103
	s_and_b64 vcc, exec, s[38:39]
	s_nop 1
	v_permlane16_swap_b32_e32 v3, v103
	s_nop 0
	v_max_f32_e32 v3, v103, v3
	v_mov_b32_e32 v78, v3
	s_nop 1
	v_permlane32_swap_b32_e32 v78, v3
	s_nop 0
	v_max3_f32 v78, v4, v3, v78
	v_max_f32_e32 v79, s97, v78
	v_sub_f32_e32 v3, v90, v79
	v_pk_add_f32 v[196:197], v[196:197], v[78:79] op_sel:[0,1] op_sel_hi:[1,1] neg_lo:[0,1] neg_hi:[0,1]
	v_sub_f32_e32 v81, v93, v79
	v_pk_add_f32 v[198:199], v[198:199], v[78:79] op_sel:[0,1] op_sel_hi:[1,1] neg_lo:[0,1] neg_hi:[0,1]
	v_pk_add_f32 v[200:201], v[200:201], v[78:79] op_sel:[0,1] op_sel_hi:[1,1] neg_lo:[0,1] neg_hi:[0,1]
	v_pk_add_f32 v[202:203], v[202:203], v[78:79] op_sel:[0,1] op_sel_hi:[1,1] neg_lo:[0,1] neg_hi:[0,1]
	v_pk_add_f32 v[204:205], v[204:205], v[78:79] op_sel:[0,1] op_sel_hi:[1,1] neg_lo:[0,1] neg_hi:[0,1]
	v_pk_add_f32 v[206:207], v[206:207], v[78:79] op_sel:[0,1] op_sel_hi:[1,1] neg_lo:[0,1] neg_hi:[0,1]
	v_pk_add_f32 v[208:209], v[208:209], v[78:79] op_sel:[0,1] op_sel_hi:[1,1] neg_lo:[0,1] neg_hi:[0,1]
	v_exp_f32_e32 v228, v3
	v_exp_f32_e32 v229, v196
	v_exp_f32_e32 v230, v197
	v_exp_f32_e32 v232, v81
	v_exp_f32_e32 v231, v198
	v_exp_f32_e32 v233, v199
	v_exp_f32_e32 v234, v200
	v_exp_f32_e32 v235, v201
	v_exp_f32_e32 v3, v202
	v_exp_f32_e32 v103, v203
	v_exp_f32_e32 v210, v204
	v_exp_f32_e32 v212, v205
	v_exp_f32_e32 v211, v206
	v_exp_f32_e32 v223, v207
	v_exp_f32_e32 v224, v208
	v_exp_f32_e32 v225, v209
	s_nop 0
	v_pk_add_f32 v[82:83], v[210:211], v[224:225]
	v_pk_add_f32 v[84:85], v[228:229], v[230:231]
	v_pk_add_f32 v[82:83], v[82:83], v[84:85]
	v_pk_add_f32 v[84:85], v[232:233], v[234:235]
	v_pk_add_f32 v[82:83], v[82:83], v[84:85]
	v_add_f32_e32 v80, v82, v83
	v_add_f32_e32 v80, v3, v80
	v_add_f32_e32 v80, v103, v80
	v_add_f32_e32 v80, v212, v80
	v_add_f32_e32 v80, v223, v80
	s_branch .LBB0_4450

.LBB0_4453:
	v_mov_b32_e32 v62, v81
	s_and_b64 vcc, exec, s[38:39]
	s_nop 1
	v_permlane16_swap_b32_e32 v62, v81
	s_nop 0
	v_max_f32_e32 v62, v81, v62
	v_mov_b32_e32 v63, v62
	s_nop 1
	v_permlane32_swap_b32_e32 v63, v62
	s_nop 0
	v_max3_f32 v79, v5, v62, v63
	v_max_f32_e32 v200, s97, v79
	v_sub_f32_e32 v62, v74, v200
	v_pk_add_f32 v[82:83], v[82:83], v[200:201] op_sel_hi:[1,0] neg_lo:[0,1] neg_hi:[0,1]
	v_sub_f32_e32 v65, v77, v200
	v_pk_add_f32 v[84:85], v[84:85], v[200:201] op_sel_hi:[1,0] neg_lo:[0,1] neg_hi:[0,1]
	v_pk_add_f32 v[86:87], v[86:87], v[200:201] op_sel_hi:[1,0] neg_lo:[0,1] neg_hi:[0,1]
	v_pk_add_f32 v[88:89], v[88:89], v[200:201] op_sel_hi:[1,0] neg_lo:[0,1] neg_hi:[0,1]
	v_pk_add_f32 v[90:91], v[90:91], v[200:201] op_sel_hi:[1,0] neg_lo:[0,1] neg_hi:[0,1]
	v_pk_add_f32 v[92:93], v[92:93], v[200:201] op_sel_hi:[1,0] neg_lo:[0,1] neg_hi:[0,1]
	v_pk_add_f32 v[196:197], v[196:197], v[200:201] op_sel_hi:[1,0] neg_lo:[0,1] neg_hi:[0,1]
	v_exp_f32_e32 v70, v62
	v_exp_f32_e32 v71, v82
	v_exp_f32_e32 v72, v83
	v_exp_f32_e32 v75, v65
	v_exp_f32_e32 v73, v84
	v_exp_f32_e32 v76, v85
	v_exp_f32_e32 v198, v86
	v_exp_f32_e32 v199, v87
	v_exp_f32_e32 v62, v88
	v_exp_f32_e32 v63, v89
	v_exp_f32_e32 v64, v90
	v_exp_f32_e32 v66, v91
	v_exp_f32_e32 v65, v92
	v_exp_f32_e32 v67, v93
	v_exp_f32_e32 v68, v196
	v_exp_f32_e32 v69, v197
	s_nop 0
	v_pk_add_f32 v[82:83], v[62:63], v[64:65]
	v_pk_add_f32 v[84:85], v[66:67], v[68:69]
	v_pk_add_f32 v[82:83], v[82:83], v[84:85]
	v_pk_add_f32 v[84:85], v[70:71], v[72:73]
	v_pk_add_f32 v[82:83], v[82:83], v[84:85]
	v_pk_add_f32 v[82:83], v[82:83], v[198:199]
	v_add_f32_e32 v81, v82, v83
	v_add_f32_e32 v81, v75, v81
	v_add_f32_e32 v81, v76, v81
	s_branch .LBB0_4456
